# first two vmcnt waits of each int8 tile's first k-iteration count the 8 epilogue stores as allowed-outstanding (vmcnt 16), so hid stores drain under the next tile's first segments
# speedup vs baseline: 1.0030x; 1.0027x over previous
; #define PG8_STAGE(bufoff, gbase, voff) do { _Pragma("unroll") for (int _i = 0; _i < 2; ++_i) \
;         __builtin_amdgcn_global_load_lds((const unsigned*)((const char*)(gbase) + (voff)[_i]), (PG8_LAS unsigned*)(lds + (bufoff) + ldsw + _i * 8192), 16, 0, 0); } while (0)
; #define PG8_LDA(dst, b, h) do { _Pragma("unroll") for (int m = 0; m < 4; ++m) _Pragma("unroll") for (int k = 0; k < 2; ++k) dst[m][k] = *(const PG8_LAS frag_t*)(lds + PG8_SA(b, h) + aoff + m * 2048 + k * 1024); } while (0)
; #define PG8_LDB(dst, b, h) do { _Pragma("unroll") for (int n = 0; n < 2; ++n) _Pragma("unroll") for (int k = 0; k < 2; ++k) dst[n][k] = *(const PG8_LAS frag_t*)(lds + PG8_SB(b, h) + boff + n * 2048 + k * 1024); } while (0)
; #define PG8_MMA(ai, bj, At, Bt) do { __builtin_amdgcn_s_setprio(1); _Pragma("unroll") for (int m = 0; m < 4; ++m) _Pragma("unroll") for (int n = 0; n < 2; ++n) _Pragma("unroll") for (int k = 0; k < 2; ++k) \
;         acc[ai][bj][m][n] = mma1v<MMAV>(Bt[n][k], At[m][k], acc[ai][bj][m][n]); __builtin_amdgcn_s_setprio(0); } while (0)
; #define PG8_WAIT_V(n) asm volatile("s_waitcnt vmcnt(" #n ")" ::: "memory")
; #define PG8_WAIT_L(n) asm volatile("s_waitcnt lgkmcnt(" #n ")" ::: "memory")
;     ...
;         const bool has_next = S.next(ui + 1, nxt);
;         const char* nA = has_next ? (const char*)g.A + (size_t)nxt.pm * tstep : cA; const char* nB = has_next ? (const char*)g.Bt + (size_t)nxt.pn * tstep : cB;
;         for (int t = 0; t < nt; t += 2) {
;             const bool last = (t == nt - 2);
;             const char* a1 = cA + (size_t)(t + 1) * kstep;
;             const char* a2 = last ? nA : cA + (size_t)(t + 2) * kstep; const char* b2 = last ? nB : cB + (size_t)(t + 2) * kstepB;
;             const char* a3 = a2 + kstep; const char* b3 = b2 + kstepB;
;             if (last && has_next) S.a_ready(nxt);
;             if constexpr (SP2) {
;             PG8_LDB(B0, 0, 0); PG8_LDB(B1, 0, 1); PG8_SCHED; PG8_LDA(At, 0, 0); PG8_STAGE(PG8_SA(1, 1), a1 + hstep, voffA);
;             PG8_WAIT_V(8); PG8_WAIT_L(0); PG8_BAR; PG8_MMA(0, 0, At, B0); PG8_MMA(0, 1, At, B1); PG8_BAR; PG8_SCHED;
;             PG8_LDA(At, 0, 1); PG8_STAGE(PG8_SB(0, 0), b2, voffB); PG8_STAGE(PG8_SB(0, 1), b2 + hstepB, voffB); PG8_STAGE(PG8_SA(0, 0), a2, voffA);
;             PG8_WAIT_V(8); PG8_WAIT_L(0); PG8_BAR; PG8_MMA(1, 0, At, B0); PG8_MMA(1, 1, At, B1); PG8_BAR; PG8_SCHED;
.LBB0_162:
	s_ashr_i32 s15, s14, 31
	s_lshl_b64 s[16:17], s[14:15], 19
	s_add_u32 s16, s0, s16
	s_addc_u32 s17, s1, s17
	s_and_b64 s[18:19], s[4:5], exec
	s_cselect_b32 s15, s17, s25
	s_cselect_b32 s49, s16, s24
	s_ashr_i32 s13, s12, 31
	s_lshl_b64 s[18:19], s[12:13], 19
	s_add_u32 s18, s34, s18
	s_addc_u32 s19, s35, s19
	s_and_b64 s[26:27], s[4:5], exec
	s_cselect_b32 s13, s19, s23
	s_cselect_b32 s50, s18, s22
	s_add_u32 s51, s22, 0x10000
	s_addc_u32 s52, s23, 0
	s_add_u32 s22, s24, 0x40080
	s_addc_u32 s23, s25, 0
	s_mov_b32 s53, -2
	s_add_u32 s24, s22, 0xfffc0080
	s_addc_u32 s25, s23, -1
	s_add_i32 s54, 0, 0x10000
	s_cmp_eq_u32 s53, 12
	s_cselect_b32 s27, s15, s25
	s_cselect_b32 s26, s49, s24
	v_add_u32_e32 v154, s54, v158
	s_cselect_b32 s25, s13, s52
	s_cselect_b32 s24, s50, s51
	s_add_i32 s56, 0, 0x14000
	ds_read_b128 v[142:145], v154
	ds_read_b128 v[146:149], v154 offset:1024
	ds_read_b128 v[150:153], v154 offset:2048
	ds_read_b128 v[174:177], v154 offset:3072
	v_add_u32_e32 v154, s56, v158
	ds_read_b128 v[178:181], v154
	ds_read_b128 v[182:185], v154 offset:1024
	ds_read_b128 v[186:189], v154 offset:2048
	ds_read_b128 v[216:219], v154 offset:3072
	v_lshl_add_u64 v[156:157], s[22:23], 0, v[138:139]
	s_add_i32 m0, s36, 0xc000
	ds_read_b128 v[220:223], v159
	ds_read_b128 v[224:227], v159 offset:1024
	ds_read_b128 v[228:231], v159 offset:2048
	ds_read_b128 v[232:235], v159 offset:3072
	ds_read_b128 v[236:239], v159 offset:4096
	ds_read_b128 v[240:243], v159 offset:5120
	ds_read_b128 v[244:247], v159 offset:6144
	ds_read_b128 v[248:251], v159 offset:7168
	global_load_lds_dwordx4 v[156:157], off
	v_lshl_add_u64 v[156:157], s[22:23], 0, v[140:141]
	s_add_i32 m0, s36, 0xe000
	s_nop 0
	global_load_lds_dwordx4 v[156:157], off
	s_waitcnt vmcnt(16)
	s_waitcnt lgkmcnt(0)
	s_barrier
	s_setprio 1
	s_waitcnt lgkmcnt(0)
	v_mfma_i32_16x16x64_i8 v[126:129], v[142:145], v[220:223], 0
	v_mfma_i32_16x16x64_i8 v[118:121], v[150:153], v[220:223], 0
	v_mfma_i32_16x16x64_i8 v[110:113], v[142:145], v[228:231], 0
	v_mfma_i32_16x16x64_i8 v[102:105], v[150:153], v[228:231], 0
	v_mfma_i32_16x16x64_i8 v[94:97], v[142:145], v[236:239], 0
	v_mfma_i32_16x16x64_i8 v[86:89], v[150:153], v[236:239], 0
	v_mfma_i32_16x16x64_i8 v[78:81], v[142:145], v[244:247], 0
	v_mfma_i32_16x16x64_i8 v[70:73], v[150:153], v[244:247], 0
	v_mfma_i32_16x16x64_i8 v[126:129], v[146:149], v[224:227], v[126:129]
	v_mfma_i32_16x16x64_i8 v[118:121], v[174:177], v[224:227], v[118:121]
	v_mfma_i32_16x16x64_i8 v[110:113], v[146:149], v[232:235], v[110:113]
	v_mfma_i32_16x16x64_i8 v[102:105], v[174:177], v[232:235], v[102:105]
	v_mfma_i32_16x16x64_i8 v[94:97], v[146:149], v[240:243], v[94:97]
	v_mfma_i32_16x16x64_i8 v[86:89], v[174:177], v[240:243], v[86:89]
	v_mfma_i32_16x16x64_i8 v[78:81], v[146:149], v[248:251], v[78:81]
	v_mfma_i32_16x16x64_i8 v[70:73], v[174:177], v[248:251], v[70:73]
	s_setprio 0
	s_setprio 1
	v_mfma_i32_16x16x64_i8 v[122:125], v[178:181], v[220:223], 0
	v_mfma_i32_16x16x64_i8 v[114:117], v[186:189], v[220:223], 0
	v_mfma_i32_16x16x64_i8 v[106:109], v[178:181], v[228:231], 0
	v_mfma_i32_16x16x64_i8 v[98:101], v[186:189], v[228:231], 0
	v_mfma_i32_16x16x64_i8 v[90:93], v[178:181], v[236:239], 0
	v_mfma_i32_16x16x64_i8 v[82:85], v[186:189], v[236:239], 0
	v_mfma_i32_16x16x64_i8 v[74:77], v[178:181], v[244:247], 0
	v_mfma_i32_16x16x64_i8 v[66:69], v[186:189], v[244:247], 0
	v_mfma_i32_16x16x64_i8 v[122:125], v[182:185], v[224:227], v[122:125]
	v_mfma_i32_16x16x64_i8 v[114:117], v[216:219], v[224:227], v[114:117]
	v_mfma_i32_16x16x64_i8 v[106:109], v[182:185], v[232:235], v[106:109]
	v_mfma_i32_16x16x64_i8 v[98:101], v[216:219], v[232:235], v[98:101]
	v_mfma_i32_16x16x64_i8 v[90:93], v[182:185], v[240:243], v[90:93]
	v_mfma_i32_16x16x64_i8 v[82:85], v[216:219], v[240:243], v[82:85]
	v_mfma_i32_16x16x64_i8 v[74:77], v[182:185], v[248:251], v[74:77]
	v_mfma_i32_16x16x64_i8 v[66:69], v[216:219], v[248:251], v[66:69]
	s_setprio 0
	s_barrier
	s_add_i32 s54, s54, s31
	v_lshl_add_u64 v[156:157], s[24:25], 0, v[134:135]
	s_mov_b32 m0, s54
	ds_read_b128 v[220:223], v159 offset:16384
	ds_read_b128 v[224:227], v159 offset:17408
	ds_read_b128 v[228:231], v159 offset:18432
	ds_read_b128 v[232:235], v159 offset:19456
	ds_read_b128 v[236:239], v159 offset:20480
	ds_read_b128 v[240:243], v159 offset:21504
	ds_read_b128 v[244:247], v159 offset:22528
	ds_read_b128 v[248:251], v159 offset:23552
	global_load_lds_dwordx4 v[156:157], off
	s_add_i32 m0, s54, 0x2000
	s_add_u32 s54, s24, 0x4000
	v_lshl_add_u64 v[156:157], s[24:25], 0, v[130:131]
	s_addc_u32 s55, s25, 0
	s_add_i32 s56, s56, s31
	global_load_lds_dwordx4 v[156:157], off
	v_lshl_add_u64 v[156:157], s[54:55], 0, v[134:135]
	s_mov_b32 m0, s56
	v_lshl_add_u64 v[160:161], s[26:27], 0, v[132:133]
	global_load_lds_dwordx4 v[156:157], off
	v_lshl_add_u64 v[156:157], s[54:55], 0, v[130:131]
	s_add_i32 m0, s56, 0x2000
	s_nop 0
	global_load_lds_dwordx4 v[156:157], off
	v_lshl_add_u64 v[156:157], s[26:27], 0, v[136:137]
	s_mov_b32 m0, s36
	s_nop 0
	global_load_lds_dwordx4 v[156:157], off
	s_mov_b32 m0, s37
	s_nop 0
	global_load_lds_dwordx4 v[160:161], off
	s_waitcnt vmcnt(16)
	s_waitcnt lgkmcnt(0)
	s_barrier
; #define PG8_STAGE(bufoff, gbase, voff) do { _Pragma("unroll") for (int _i = 0; _i < 2; ++_i) \
;         __builtin_amdgcn_global_load_lds((const unsigned*)((const char*)(gbase) + (voff)[_i]), (PG8_LAS unsigned*)(lds + (bufoff) + ldsw + _i * 8192), 16, 0, 0); } while (0)
; #define PG8_LDA(dst, b, h) do { _Pragma("unroll") for (int m = 0; m < 4; ++m) _Pragma("unroll") for (int k = 0; k < 2; ++k) dst[m][k] = *(const PG8_LAS frag_t*)(lds + PG8_SA(b, h) + aoff + m * 2048 + k * 1024); } while (0)
; #define PG8_LDB(dst, b, h) do { _Pragma("unroll") for (int n = 0; n < 2; ++n) _Pragma("unroll") for (int k = 0; k < 2; ++k) dst[n][k] = *(const PG8_LAS frag_t*)(lds + PG8_SB(b, h) + boff + n * 2048 + k * 1024); } while (0)
; #define PG8_MMA(ai, bj, At, Bt) do { __builtin_amdgcn_s_setprio(1); _Pragma("unroll") for (int m = 0; m < 4; ++m) _Pragma("unroll") for (int n = 0; n < 2; ++n) _Pragma("unroll") for (int k = 0; k < 2; ++k) \
;         acc[ai][bj][m][n] = mma1v<MMAV>(Bt[n][k], At[m][k], acc[ai][bj][m][n]); __builtin_amdgcn_s_setprio(0); } while (0)
; #define PG8_WAIT_V(n) asm volatile("s_waitcnt vmcnt(" #n ")" ::: "memory")
; #define PG8_WAIT_L(n) asm volatile("s_waitcnt lgkmcnt(" #n ")" ::: "memory")
; #define PG8_BAR __builtin_amdgcn_s_barrier()
; #define PG8_SCHED __builtin_amdgcn_sched_barrier(0)
;     ...
;             PG8_WAIT_V(8); PG8_WAIT_L(0); PG8_BAR; PG8_MMA(1, 0, At, B0); PG8_MMA(1, 1, At, B1); PG8_BAR; PG8_SCHED;
;             PG8_LDB(B0, 1, 0); PG8_LDB(B1, 1, 1); PG8_SCHED; PG8_LDA(At, 1, 0); PG8_STAGE(PG8_SA(0, 1), a2 + hstep, voffA);
;             PG8_WAIT_V(8); PG8_WAIT_L(0); PG8_BAR; PG8_MMA(0, 0, At, B0); PG8_MMA(0, 1, At, B1); PG8_BAR; PG8_SCHED;
;             PG8_LDA(At, 1, 1); PG8_STAGE(PG8_SB(1, 0), b3, voffB); PG8_STAGE(PG8_SB(1, 1), b3 + hstepB, voffB); PG8_STAGE(PG8_SA(1, 0), a3, voffA);
;             PG8_WAIT_V(8); PG8_WAIT_L(0); PG8_BAR; PG8_MMA(1, 0, At, B0); PG8_MMA(1, 1, At, B1); PG8_BAR; PG8_SCHED;
	s_setprio 1
	s_waitcnt lgkmcnt(0)
	v_mfma_i32_16x16x64_i8 v[62:65], v[142:145], v[220:223], 0
	v_mfma_i32_16x16x64_i8 v[54:57], v[150:153], v[220:223], 0
	v_mfma_i32_16x16x64_i8 v[46:49], v[142:145], v[228:231], 0
	v_mfma_i32_16x16x64_i8 v[38:41], v[150:153], v[228:231], 0
	v_mfma_i32_16x16x64_i8 v[30:33], v[142:145], v[236:239], 0
	v_mfma_i32_16x16x64_i8 v[22:25], v[150:153], v[236:239], 0
	v_mfma_i32_16x16x64_i8 v[14:17], v[142:145], v[244:247], 0
	v_mfma_i32_16x16x64_i8 v[6:9], v[150:153], v[244:247], 0
	v_mfma_i32_16x16x64_i8 v[62:65], v[146:149], v[224:227], v[62:65]
	v_mfma_i32_16x16x64_i8 v[54:57], v[174:177], v[224:227], v[54:57]
	v_mfma_i32_16x16x64_i8 v[46:49], v[146:149], v[232:235], v[46:49]
	v_mfma_i32_16x16x64_i8 v[38:41], v[174:177], v[232:235], v[38:41]
	v_mfma_i32_16x16x64_i8 v[30:33], v[146:149], v[240:243], v[30:33]
	v_mfma_i32_16x16x64_i8 v[22:25], v[174:177], v[240:243], v[22:25]
	v_mfma_i32_16x16x64_i8 v[14:17], v[146:149], v[248:251], v[14:17]
	v_mfma_i32_16x16x64_i8 v[6:9], v[174:177], v[248:251], v[6:9]
	s_setprio 0
	s_setprio 1
	v_mfma_i32_16x16x64_i8 v[58:61], v[178:181], v[220:223], 0
	v_mfma_i32_16x16x64_i8 v[50:53], v[186:189], v[220:223], 0
	v_mfma_i32_16x16x64_i8 v[42:45], v[178:181], v[228:231], 0
	v_mfma_i32_16x16x64_i8 v[34:37], v[186:189], v[228:231], 0
	v_mfma_i32_16x16x64_i8 v[26:29], v[178:181], v[236:239], 0
	v_mfma_i32_16x16x64_i8 v[18:21], v[186:189], v[236:239], 0
	v_mfma_i32_16x16x64_i8 v[10:13], v[178:181], v[244:247], 0
	v_mfma_i32_16x16x64_i8 v[2:5], v[186:189], v[244:247], 0
	v_mfma_i32_16x16x64_i8 v[58:61], v[182:185], v[224:227], v[58:61]
	v_mfma_i32_16x16x64_i8 v[50:53], v[216:219], v[224:227], v[50:53]
	v_mfma_i32_16x16x64_i8 v[42:45], v[182:185], v[232:235], v[42:45]
	v_mfma_i32_16x16x64_i8 v[34:37], v[216:219], v[232:235], v[34:37]
	v_mfma_i32_16x16x64_i8 v[26:29], v[182:185], v[240:243], v[26:29]
	v_mfma_i32_16x16x64_i8 v[18:21], v[216:219], v[240:243], v[18:21]
	v_mfma_i32_16x16x64_i8 v[10:13], v[182:185], v[248:251], v[10:13]
	v_mfma_i32_16x16x64_i8 v[2:5], v[216:219], v[248:251], v[2:5]
	s_setprio 0
	s_barrier
	s_add_i32 s54, 0, 0x18000
	v_add_u32_e32 v154, s54, v158
	s_add_i32 s55, 0, 0x1c000
	ds_read_b128 v[142:145], v154
	ds_read_b128 v[146:149], v154 offset:1024
	ds_read_b128 v[150:153], v154 offset:2048
	ds_read_b128 v[174:177], v154 offset:3072
	v_add_u32_e32 v154, s55, v158
	ds_read_b128 v[178:181], v154
	ds_read_b128 v[182:185], v154 offset:1024
	ds_read_b128 v[186:189], v154 offset:2048
	ds_read_b128 v[216:219], v154 offset:3072
	s_add_u32 s26, s26, 0x40000
	s_addc_u32 s27, s27, 0
	s_mov_b32 m0, s38
	v_lshl_add_u64 v[190:191], s[26:27], 0, v[136:137]
	ds_read_b128 v[220:223], v159 offset:32768
	ds_read_b128 v[224:227], v159 offset:33792
	ds_read_b128 v[228:231], v159 offset:34816
	ds_read_b128 v[232:235], v159 offset:35840
	ds_read_b128 v[236:239], v159 offset:36864
	ds_read_b128 v[240:243], v159 offset:37888
	ds_read_b128 v[244:247], v159 offset:38912
	ds_read_b128 v[248:251], v159 offset:39936
	global_load_lds_dwordx4 v[190:191], off
	v_lshl_add_u64 v[190:191], s[26:27], 0, v[132:133]
	s_mov_b32 m0, s39
	s_nop 0
	global_load_lds_dwordx4 v[190:191], off
	s_waitcnt vmcnt(8)
	s_waitcnt lgkmcnt(0)
	s_barrier
	s_setprio 1
	s_waitcnt lgkmcnt(0)
	v_mfma_i32_16x16x64_i8 v[126:129], v[142:145], v[220:223], v[126:129]
	v_mfma_i32_16x16x64_i8 v[118:121], v[150:153], v[220:223], v[118:121]
	v_mfma_i32_16x16x64_i8 v[110:113], v[142:145], v[228:231], v[110:113]
	v_mfma_i32_16x16x64_i8 v[102:105], v[150:153], v[228:231], v[102:105]
	v_mfma_i32_16x16x64_i8 v[94:97], v[142:145], v[236:239], v[94:97]
	v_mfma_i32_16x16x64_i8 v[86:89], v[150:153], v[236:239], v[86:89]
	v_mfma_i32_16x16x64_i8 v[78:81], v[142:145], v[244:247], v[78:81]
	v_mfma_i32_16x16x64_i8 v[70:73], v[150:153], v[244:247], v[70:73]
	v_mfma_i32_16x16x64_i8 v[126:129], v[146:149], v[224:227], v[126:129]
	v_mfma_i32_16x16x64_i8 v[118:121], v[174:177], v[224:227], v[118:121]
	v_mfma_i32_16x16x64_i8 v[110:113], v[146:149], v[232:235], v[110:113]
	v_mfma_i32_16x16x64_i8 v[102:105], v[174:177], v[232:235], v[102:105]
	v_mfma_i32_16x16x64_i8 v[94:97], v[146:149], v[240:243], v[94:97]
	v_mfma_i32_16x16x64_i8 v[86:89], v[174:177], v[240:243], v[86:89]
	v_mfma_i32_16x16x64_i8 v[78:81], v[146:149], v[248:251], v[78:81]
	v_mfma_i32_16x16x64_i8 v[70:73], v[174:177], v[248:251], v[70:73]
	s_setprio 0
	s_setprio 1
	v_mfma_i32_16x16x64_i8 v[122:125], v[178:181], v[220:223], v[122:125]
	v_mfma_i32_16x16x64_i8 v[114:117], v[186:189], v[220:223], v[114:117]
	v_mfma_i32_16x16x64_i8 v[106:109], v[178:181], v[228:231], v[106:109]
	v_mfma_i32_16x16x64_i8 v[98:101], v[186:189], v[228:231], v[98:101]
	v_mfma_i32_16x16x64_i8 v[90:93], v[178:181], v[236:239], v[90:93]
	v_mfma_i32_16x16x64_i8 v[82:85], v[186:189], v[236:239], v[82:85]
	v_mfma_i32_16x16x64_i8 v[74:77], v[178:181], v[244:247], v[74:77]
	v_mfma_i32_16x16x64_i8 v[66:69], v[186:189], v[244:247], v[66:69]
	v_mfma_i32_16x16x64_i8 v[122:125], v[182:185], v[224:227], v[122:125]
	v_mfma_i32_16x16x64_i8 v[114:117], v[216:219], v[224:227], v[114:117]
	v_mfma_i32_16x16x64_i8 v[106:109], v[182:185], v[232:235], v[106:109]
	v_mfma_i32_16x16x64_i8 v[98:101], v[216:219], v[232:235], v[98:101]
	v_mfma_i32_16x16x64_i8 v[90:93], v[182:185], v[240:243], v[90:93]
	v_mfma_i32_16x16x64_i8 v[82:85], v[216:219], v[240:243], v[82:85]
	v_mfma_i32_16x16x64_i8 v[74:77], v[182:185], v[248:251], v[74:77]
	v_mfma_i32_16x16x64_i8 v[66:69], v[216:219], v[248:251], v[66:69]
	s_setprio 0
	s_barrier
; #define PG8_STAGE(bufoff, gbase, voff) do { _Pragma("unroll") for (int _i = 0; _i < 2; ++_i) \
;         __builtin_amdgcn_global_load_lds((const unsigned*)((const char*)(gbase) + (voff)[_i]), (PG8_LAS unsigned*)(lds + (bufoff) + ldsw + _i * 8192), 16, 0, 0); } while (0)
; #define PG8_LDA(dst, b, h) do { _Pragma("unroll") for (int m = 0; m < 4; ++m) _Pragma("unroll") for (int k = 0; k < 2; ++k) dst[m][k] = *(const PG8_LAS frag_t*)(lds + PG8_SA(b, h) + aoff + m * 2048 + k * 1024); } while (0)
; #define PG8_MMA(ai, bj, At, Bt) do { __builtin_amdgcn_s_setprio(1); _Pragma("unroll") for (int m = 0; m < 4; ++m) _Pragma("unroll") for (int n = 0; n < 2; ++n) _Pragma("unroll") for (int k = 0; k < 2; ++k) \
;         acc[ai][bj][m][n] = mma1v<MMAV>(Bt[n][k], At[m][k], acc[ai][bj][m][n]); __builtin_amdgcn_s_setprio(0); } while (0)
; #define PG8_WAIT_V(n) asm volatile("s_waitcnt vmcnt(" #n ")" ::: "memory")
; #define PG8_WAIT_L(n) asm volatile("s_waitcnt lgkmcnt(" #n ")" ::: "memory")
; #define PG8_BAR __builtin_amdgcn_s_barrier()
; #define PG8_SCHED __builtin_amdgcn_sched_barrier(0)
;     ...
;             PG8_WAIT_V(8); PG8_WAIT_L(0); PG8_BAR; PG8_MMA(0, 0, At, B0); PG8_MMA(0, 1, At, B1); PG8_BAR; PG8_SCHED;
;             PG8_LDA(At, 1, 1); PG8_STAGE(PG8_SB(1, 0), b3, voffB); PG8_STAGE(PG8_SB(1, 1), b3 + hstepB, voffB); PG8_STAGE(PG8_SA(1, 0), a3, voffA);
;             PG8_WAIT_V(8); PG8_WAIT_L(0); PG8_BAR; PG8_MMA(1, 0, At, B0); PG8_MMA(1, 1, At, B1); PG8_BAR; PG8_SCHED;
	s_add_u32 s26, s24, 0x8000
	s_addc_u32 s27, s25, 0
	s_add_i32 s54, s54, s31
	v_lshl_add_u64 v[190:191], s[26:27], 0, v[134:135]
	s_mov_b32 m0, s54
	ds_read_b128 v[220:223], v159 offset:49152
	ds_read_b128 v[224:227], v159 offset:50176
	ds_read_b128 v[228:231], v159 offset:51200
	ds_read_b128 v[232:235], v159 offset:52224
	ds_read_b128 v[236:239], v159 offset:53248
	ds_read_b128 v[240:243], v159 offset:54272
	ds_read_b128 v[244:247], v159 offset:55296
	ds_read_b128 v[248:251], v159 offset:56320
	global_load_lds_dwordx4 v[190:191], off
	s_add_i32 m0, s54, 0x2000
	s_add_u32 s24, s24, 0xc000
	v_lshl_add_u64 v[190:191], s[26:27], 0, v[130:131]
	s_addc_u32 s25, s25, 0
	s_add_i32 s26, s55, s31
	global_load_lds_dwordx4 v[190:191], off
	v_lshl_add_u64 v[190:191], s[24:25], 0, v[134:135]
	s_mov_b32 m0, s26
	v_lshl_add_u64 v[156:157], v[156:157], 0, s[78:79]
	global_load_lds_dwordx4 v[190:191], off
	v_lshl_add_u64 v[190:191], s[24:25], 0, v[130:131]
	s_add_i32 m0, s26, 0x2000
	s_nop 0
	global_load_lds_dwordx4 v[190:191], off
	s_mov_b32 m0, s42
	s_nop 0
	global_load_lds_dwordx4 v[156:157], off
	v_lshl_add_u64 v[156:157], v[160:161], 0, s[78:79]
	s_mov_b32 m0, s43
	s_nop 0
	global_load_lds_dwordx4 v[156:157], off
	s_waitcnt vmcnt(8)
	s_waitcnt lgkmcnt(0)
	s_barrier
	s_setprio 1
	s_waitcnt lgkmcnt(0)
	v_mfma_i32_16x16x64_i8 v[62:65], v[142:145], v[220:223], v[62:65]
	v_mfma_i32_16x16x64_i8 v[54:57], v[150:153], v[220:223], v[54:57]
	v_mfma_i32_16x16x64_i8 v[46:49], v[142:145], v[228:231], v[46:49]
	v_mfma_i32_16x16x64_i8 v[38:41], v[150:153], v[228:231], v[38:41]
	v_mfma_i32_16x16x64_i8 v[30:33], v[142:145], v[236:239], v[30:33]
	v_mfma_i32_16x16x64_i8 v[22:25], v[150:153], v[236:239], v[22:25]
	v_mfma_i32_16x16x64_i8 v[14:17], v[142:145], v[244:247], v[14:17]
	v_mfma_i32_16x16x64_i8 v[6:9], v[150:153], v[244:247], v[6:9]
	v_mfma_i32_16x16x64_i8 v[62:65], v[146:149], v[224:227], v[62:65]
	v_mfma_i32_16x16x64_i8 v[54:57], v[174:177], v[224:227], v[54:57]
	v_mfma_i32_16x16x64_i8 v[46:49], v[146:149], v[232:235], v[46:49]
	v_mfma_i32_16x16x64_i8 v[38:41], v[174:177], v[232:235], v[38:41]
	v_mfma_i32_16x16x64_i8 v[30:33], v[146:149], v[240:243], v[30:33]
	v_mfma_i32_16x16x64_i8 v[22:25], v[174:177], v[240:243], v[22:25]
	v_mfma_i32_16x16x64_i8 v[14:17], v[146:149], v[248:251], v[14:17]
	v_mfma_i32_16x16x64_i8 v[6:9], v[174:177], v[248:251], v[6:9]
	s_setprio 0
	s_setprio 1
	v_mfma_i32_16x16x64_i8 v[58:61], v[178:181], v[220:223], v[58:61]
	v_mfma_i32_16x16x64_i8 v[50:53], v[186:189], v[220:223], v[50:53]
	v_mfma_i32_16x16x64_i8 v[42:45], v[178:181], v[228:231], v[42:45]
	v_mfma_i32_16x16x64_i8 v[34:37], v[186:189], v[228:231], v[34:37]
	v_mfma_i32_16x16x64_i8 v[26:29], v[178:181], v[236:239], v[26:29]
	v_mfma_i32_16x16x64_i8 v[18:21], v[186:189], v[236:239], v[18:21]
	v_mfma_i32_16x16x64_i8 v[10:13], v[178:181], v[244:247], v[10:13]
	v_mfma_i32_16x16x64_i8 v[2:5], v[186:189], v[244:247], v[2:5]
	v_mfma_i32_16x16x64_i8 v[58:61], v[182:185], v[224:227], v[58:61]
	v_mfma_i32_16x16x64_i8 v[50:53], v[216:219], v[224:227], v[50:53]
	v_mfma_i32_16x16x64_i8 v[42:45], v[182:185], v[232:235], v[42:45]
	v_mfma_i32_16x16x64_i8 v[34:37], v[216:219], v[232:235], v[34:37]
	v_mfma_i32_16x16x64_i8 v[26:29], v[182:185], v[240:243], v[26:29]
	v_mfma_i32_16x16x64_i8 v[18:21], v[216:219], v[240:243], v[18:21]
	v_mfma_i32_16x16x64_i8 v[10:13], v[182:185], v[248:251], v[10:13]
	v_mfma_i32_16x16x64_i8 v[2:5], v[216:219], v[248:251], v[2:5]
	s_setprio 0
	s_barrier
	s_add_i32 s53, s53, 2
	s_add_u32 s51, s51, 0x10000
	s_addc_u32 s52, s52, 0
	s_add_u32 s22, s22, 0x100
	s_addc_u32 s23, s23, 0
